# E1 plus SP1-segment LDS-DMA in the input and gate/up projection loops switched to the saddr form (SGPR base + 32-bit lane offset, no per-DMA 64-bit VALU add)
# speedup vs baseline: 1.0193x; 1.0193x over previous
.LBB0_264:
	s_or_b32 s22, s56, 1
	s_lshl_b64 s[2:3], s[22:23], 7
	s_add_u32 s58, s76, s2
	s_addc_u32 s68, s77, s3
	s_add_i32 s22, s56, 2
	s_lshl_b64 s[38:39], s[22:23], 7
	s_add_u32 s69, s76, s38
	s_addc_u32 s72, s77, s39
	s_and_b64 s[2:3], s[28:29], exec
	s_cselect_b32 s3, s72, s11
	s_cselect_b32 s2, s69, s45
	s_add_u32 s38, s26, s38
	s_addc_u32 s39, s27, s39
	s_and_b64 s[28:29], s[28:29], exec
	s_cselect_b32 s29, s39, s31
	s_cselect_b32 s28, s38, s54
	s_add_i32 s69, 0, 0x10000
	s_add_i32 s72, 0, 0x14000
	v_add_u32_e32 v152, s69, v160
	v_add_u32_e32 v156, s72, v160
	ds_read_b128 v[140:143], v152
	ds_read_b128 v[144:147], v152 offset:1024
	ds_read_b128 v[148:151], v152 offset:2048
	ds_read_b128 v[152:155], v152 offset:3072
	ds_read_b128 v[168:171], v156
	ds_read_b128 v[172:175], v156 offset:1024
	ds_read_b128 v[176:179], v156 offset:2048
	ds_read_b128 v[180:183], v156 offset:3072
	s_add_u32 s38, s58, 0x80000
	s_addc_u32 s39, s68, 0
	s_add_i32 m0, s93, 0xc000
	ds_read_b128 v[184:187], v166
	ds_read_b128 v[188:191], v166 offset:1024
	ds_read_b128 v[192:195], v166 offset:2048
	ds_read_b128 v[196:199], v166 offset:3072
	ds_read_b128 v[226:229], v166 offset:4096
	ds_read_b128 v[230:233], v166 offset:5120
	ds_read_b128 v[234:237], v166 offset:6144
	ds_read_b128 v[238:241], v166 offset:7168
	global_load_lds_dwordx4 v130, s[38:39]
	s_add_i32 m0, s93, 0xe000
	s_nop 0
	global_load_lds_dwordx4 v134, s[38:39]
	s_waitcnt vmcnt(8)
	s_waitcnt lgkmcnt(0)
	s_barrier
	s_setprio 1
	v_mfma_f32_16x16x32_bf16 v[126:129], v[140:143], v[184:187], v[126:129]
	v_mfma_f32_16x16x32_bf16 v[122:125], v[148:151], v[184:187], v[122:125]
	v_mfma_f32_16x16x32_bf16 v[110:113], v[140:143], v[192:195], v[110:113]
	v_mfma_f32_16x16x32_bf16 v[106:109], v[148:151], v[192:195], v[106:109]
	v_mfma_f32_16x16x32_bf16 v[94:97], v[140:143], v[226:229], v[94:97]
	v_mfma_f32_16x16x32_bf16 v[90:93], v[148:151], v[226:229], v[90:93]
	v_mfma_f32_16x16x32_bf16 v[78:81], v[140:143], v[234:237], v[78:81]
	v_mfma_f32_16x16x32_bf16 v[74:77], v[148:151], v[234:237], v[74:77]
	v_mfma_f32_16x16x32_bf16 v[126:129], v[144:147], v[188:191], v[126:129]
	v_mfma_f32_16x16x32_bf16 v[122:125], v[152:155], v[188:191], v[122:125]
	v_mfma_f32_16x16x32_bf16 v[110:113], v[144:147], v[196:199], v[110:113]
	v_mfma_f32_16x16x32_bf16 v[106:109], v[152:155], v[196:199], v[106:109]
	v_mfma_f32_16x16x32_bf16 v[94:97], v[144:147], v[230:233], v[94:97]
	v_mfma_f32_16x16x32_bf16 v[90:93], v[152:155], v[230:233], v[90:93]
	v_mfma_f32_16x16x32_bf16 v[78:81], v[144:147], v[238:241], v[78:81]
	v_mfma_f32_16x16x32_bf16 v[74:77], v[152:155], v[238:241], v[74:77]
	v_mfma_f32_16x16x32_bf16 v[118:121], v[168:171], v[184:187], v[118:121]
	v_mfma_f32_16x16x32_bf16 v[114:117], v[176:179], v[184:187], v[114:117]
	v_mfma_f32_16x16x32_bf16 v[102:105], v[168:171], v[192:195], v[102:105]
	v_mfma_f32_16x16x32_bf16 v[98:101], v[176:179], v[192:195], v[98:101]
	v_mfma_f32_16x16x32_bf16 v[86:89], v[168:171], v[226:229], v[86:89]
	v_mfma_f32_16x16x32_bf16 v[82:85], v[176:179], v[226:229], v[82:85]
	v_mfma_f32_16x16x32_bf16 v[70:73], v[168:171], v[234:237], v[70:73]
	v_mfma_f32_16x16x32_bf16 v[66:69], v[176:179], v[234:237], v[66:69]
	v_mfma_f32_16x16x32_bf16 v[118:121], v[172:175], v[188:191], v[118:121]
	v_mfma_f32_16x16x32_bf16 v[114:117], v[180:183], v[188:191], v[114:117]
	v_mfma_f32_16x16x32_bf16 v[102:105], v[172:175], v[196:199], v[102:105]
	v_mfma_f32_16x16x32_bf16 v[98:101], v[180:183], v[196:199], v[98:101]
	v_mfma_f32_16x16x32_bf16 v[86:89], v[172:175], v[230:233], v[86:89]
	v_mfma_f32_16x16x32_bf16 v[82:85], v[180:183], v[230:233], v[82:85]
	v_mfma_f32_16x16x32_bf16 v[70:73], v[172:175], v[238:241], v[70:73]
	v_mfma_f32_16x16x32_bf16 v[66:69], v[180:183], v[238:241], v[66:69]
	s_setprio 0
	s_barrier
	s_add_i32 s38, s69, s21
	v_lshl_add_u64 v[156:157], s[28:29], 0, v[132:133]
	s_mov_b32 m0, s38
	ds_read_b128 v[184:187], v166 offset:16384
	ds_read_b128 v[188:191], v166 offset:17408
	ds_read_b128 v[192:195], v166 offset:18432
	ds_read_b128 v[196:199], v166 offset:19456
	ds_read_b128 v[226:229], v166 offset:20480
	ds_read_b128 v[230:233], v166 offset:21504
	ds_read_b128 v[234:237], v166 offset:22528
	ds_read_b128 v[238:241], v166 offset:23552
	global_load_lds_dwordx4 v[156:157], off
	s_add_i32 m0, s38, 0x2000
	s_add_u32 s38, s28, 0x80000
	v_lshl_add_u64 v[200:201], s[28:29], 0, v[136:137]
	s_addc_u32 s39, s29, 0
	s_add_i32 s58, s72, s21
	global_load_lds_dwordx4 v[200:201], off
	v_lshl_add_u64 v[206:207], s[38:39], 0, v[132:133]
	s_mov_b32 m0, s58
	v_lshl_add_u64 v[242:243], s[2:3], 0, v[134:135]
	global_load_lds_dwordx4 v[206:207], off
	v_lshl_add_u64 v[206:207], s[38:39], 0, v[136:137]
	s_add_i32 m0, s58, 0x2000
	s_nop 0
	global_load_lds_dwordx4 v[206:207], off
	v_lshl_add_u64 v[206:207], s[2:3], 0, v[130:131]
	s_mov_b32 m0, s93
	s_nop 0
	global_load_lds_dwordx4 v[206:207], off
	s_mov_b32 m0, s12
	s_nop 0
	global_load_lds_dwordx4 v[242:243], off
	s_waitcnt vmcnt(8)
	s_waitcnt lgkmcnt(0)
	s_barrier
	s_setprio 1
	v_mfma_f32_16x16x32_bf16 v[62:65], v[140:143], v[184:187], v[62:65]
	v_mfma_f32_16x16x32_bf16 v[58:61], v[148:151], v[184:187], v[58:61]
	v_mfma_f32_16x16x32_bf16 v[46:49], v[140:143], v[192:195], v[46:49]
	v_mfma_f32_16x16x32_bf16 v[42:45], v[148:151], v[192:195], v[42:45]
	v_mfma_f32_16x16x32_bf16 v[30:33], v[140:143], v[226:229], v[30:33]
	v_mfma_f32_16x16x32_bf16 v[26:29], v[148:151], v[226:229], v[26:29]
	v_mfma_f32_16x16x32_bf16 v[14:17], v[140:143], v[234:237], v[14:17]
	v_mfma_f32_16x16x32_bf16 v[10:13], v[148:151], v[234:237], v[10:13]
	v_mfma_f32_16x16x32_bf16 v[62:65], v[144:147], v[188:191], v[62:65]
	v_mfma_f32_16x16x32_bf16 v[58:61], v[152:155], v[188:191], v[58:61]
	v_mfma_f32_16x16x32_bf16 v[46:49], v[144:147], v[196:199], v[46:49]
	v_mfma_f32_16x16x32_bf16 v[42:45], v[152:155], v[196:199], v[42:45]
	v_mfma_f32_16x16x32_bf16 v[30:33], v[144:147], v[230:233], v[30:33]
	v_mfma_f32_16x16x32_bf16 v[26:29], v[152:155], v[230:233], v[26:29]
	v_mfma_f32_16x16x32_bf16 v[14:17], v[144:147], v[238:241], v[14:17]
	v_mfma_f32_16x16x32_bf16 v[10:13], v[152:155], v[238:241], v[10:13]
	v_mfma_f32_16x16x32_bf16 v[54:57], v[168:171], v[184:187], v[54:57]
	v_mfma_f32_16x16x32_bf16 v[50:53], v[176:179], v[184:187], v[50:53]
	v_mfma_f32_16x16x32_bf16 v[38:41], v[168:171], v[192:195], v[38:41]
	v_mfma_f32_16x16x32_bf16 v[34:37], v[176:179], v[192:195], v[34:37]
	v_mfma_f32_16x16x32_bf16 v[22:25], v[168:171], v[226:229], v[22:25]
	v_mfma_f32_16x16x32_bf16 v[18:21], v[176:179], v[226:229], v[18:21]
	v_mfma_f32_16x16x32_bf16 v[6:9], v[168:171], v[234:237], v[6:9]
	v_mfma_f32_16x16x32_bf16 v[2:5], v[176:179], v[234:237], v[2:5]
	v_mfma_f32_16x16x32_bf16 v[54:57], v[172:175], v[188:191], v[54:57]
	v_mfma_f32_16x16x32_bf16 v[50:53], v[180:183], v[188:191], v[50:53]
	v_mfma_f32_16x16x32_bf16 v[38:41], v[172:175], v[196:199], v[38:41]
	v_mfma_f32_16x16x32_bf16 v[34:37], v[180:183], v[196:199], v[34:37]
	v_mfma_f32_16x16x32_bf16 v[22:25], v[172:175], v[230:233], v[22:25]
	v_mfma_f32_16x16x32_bf16 v[18:21], v[180:183], v[230:233], v[18:21]
	v_mfma_f32_16x16x32_bf16 v[6:9], v[172:175], v[238:241], v[6:9]
	v_mfma_f32_16x16x32_bf16 v[2:5], v[180:183], v[238:241], v[2:5]
	s_setprio 0
	s_barrier
	s_add_i32 s38, 0, 0x18000
	s_add_i32 s39, 0, 0x1c000
	v_add_u32_e32 v152, s38, v160
	v_add_u32_e32 v167, s39, v160
	ds_read_b128 v[140:143], v152
	ds_read_b128 v[144:147], v152 offset:1024
	ds_read_b128 v[148:151], v152 offset:2048
	ds_read_b128 v[152:155], v152 offset:3072
	ds_read_b128 v[168:171], v167
	ds_read_b128 v[172:175], v167 offset:1024
	ds_read_b128 v[176:179], v167 offset:2048
	ds_read_b128 v[180:183], v167 offset:3072
	s_add_u32 s2, s2, 0x80000
	s_addc_u32 s3, s3, 0
	s_mov_b32 m0, s51
	ds_read_b128 v[184:187], v166 offset:32768
	ds_read_b128 v[188:191], v166 offset:33792
	ds_read_b128 v[192:195], v166 offset:34816
	ds_read_b128 v[196:199], v166 offset:35840
	ds_read_b128 v[226:229], v166 offset:36864
	ds_read_b128 v[230:233], v166 offset:37888
	ds_read_b128 v[234:237], v166 offset:38912
	ds_read_b128 v[238:241], v166 offset:39936
	global_load_lds_dwordx4 v130, s[2:3]
	s_mov_b32 m0, s14
	s_nop 0
	global_load_lds_dwordx4 v134, s[2:3]
	s_waitcnt vmcnt(8)
	s_waitcnt lgkmcnt(0)
	s_barrier
	s_setprio 1
	v_mfma_f32_16x16x32_bf16 v[126:129], v[140:143], v[184:187], v[126:129]
	v_mfma_f32_16x16x32_bf16 v[122:125], v[148:151], v[184:187], v[122:125]
	v_mfma_f32_16x16x32_bf16 v[110:113], v[140:143], v[192:195], v[110:113]
	v_mfma_f32_16x16x32_bf16 v[106:109], v[148:151], v[192:195], v[106:109]
	v_mfma_f32_16x16x32_bf16 v[94:97], v[140:143], v[226:229], v[94:97]
	v_mfma_f32_16x16x32_bf16 v[90:93], v[148:151], v[226:229], v[90:93]
	v_mfma_f32_16x16x32_bf16 v[78:81], v[140:143], v[234:237], v[78:81]
	v_mfma_f32_16x16x32_bf16 v[74:77], v[148:151], v[234:237], v[74:77]
	v_mfma_f32_16x16x32_bf16 v[126:129], v[144:147], v[188:191], v[126:129]
	v_mfma_f32_16x16x32_bf16 v[122:125], v[152:155], v[188:191], v[122:125]
	v_mfma_f32_16x16x32_bf16 v[110:113], v[144:147], v[196:199], v[110:113]
	v_mfma_f32_16x16x32_bf16 v[106:109], v[152:155], v[196:199], v[106:109]
	v_mfma_f32_16x16x32_bf16 v[94:97], v[144:147], v[230:233], v[94:97]
	v_mfma_f32_16x16x32_bf16 v[90:93], v[152:155], v[230:233], v[90:93]
	v_mfma_f32_16x16x32_bf16 v[78:81], v[144:147], v[238:241], v[78:81]
	v_mfma_f32_16x16x32_bf16 v[74:77], v[152:155], v[238:241], v[74:77]
	v_mfma_f32_16x16x32_bf16 v[118:121], v[168:171], v[184:187], v[118:121]
	v_mfma_f32_16x16x32_bf16 v[114:117], v[176:179], v[184:187], v[114:117]
	v_mfma_f32_16x16x32_bf16 v[102:105], v[168:171], v[192:195], v[102:105]
	v_mfma_f32_16x16x32_bf16 v[98:101], v[176:179], v[192:195], v[98:101]
	v_mfma_f32_16x16x32_bf16 v[86:89], v[168:171], v[226:229], v[86:89]
	v_mfma_f32_16x16x32_bf16 v[82:85], v[176:179], v[226:229], v[82:85]
	v_mfma_f32_16x16x32_bf16 v[70:73], v[168:171], v[234:237], v[70:73]
	v_mfma_f32_16x16x32_bf16 v[66:69], v[176:179], v[234:237], v[66:69]
	v_mfma_f32_16x16x32_bf16 v[118:121], v[172:175], v[188:191], v[118:121]
	v_mfma_f32_16x16x32_bf16 v[114:117], v[180:183], v[188:191], v[114:117]
	v_mfma_f32_16x16x32_bf16 v[102:105], v[172:175], v[196:199], v[102:105]
	v_mfma_f32_16x16x32_bf16 v[98:101], v[180:183], v[196:199], v[98:101]
	v_mfma_f32_16x16x32_bf16 v[86:89], v[172:175], v[230:233], v[86:89]
	v_mfma_f32_16x16x32_bf16 v[82:85], v[180:183], v[230:233], v[82:85]
	v_mfma_f32_16x16x32_bf16 v[70:73], v[172:175], v[238:241], v[70:73]
	v_mfma_f32_16x16x32_bf16 v[66:69], v[180:183], v[238:241], v[66:69]
	s_setprio 0
	s_barrier
	s_add_i32 s2, s38, s21
	v_lshl_add_u64 v[156:157], v[156:157], 0, s[42:43]
	s_mov_b32 m0, s2
	ds_read_b128 v[184:187], v166 offset:49152
	ds_read_b128 v[188:191], v166 offset:50176
	ds_read_b128 v[192:195], v166 offset:51200
	ds_read_b128 v[196:199], v166 offset:52224
	ds_read_b128 v[226:229], v166 offset:53248
	ds_read_b128 v[230:233], v166 offset:54272
	ds_read_b128 v[234:237], v166 offset:55296
	ds_read_b128 v[238:241], v166 offset:56320
	global_load_lds_dwordx4 v[156:157], off
	s_add_i32 m0, s2, 0x2000
	s_add_u32 s2, s28, 0x80080
	v_lshl_add_u64 v[156:157], v[200:201], 0, s[42:43]
	s_addc_u32 s3, s29, 0
	s_add_i32 s28, s39, s21
	global_load_lds_dwordx4 v[156:157], off
	v_lshl_add_u64 v[156:157], s[2:3], 0, v[132:133]
	s_mov_b32 m0, s28
	s_nop 0
	global_load_lds_dwordx4 v[156:157], off
	v_lshl_add_u64 v[156:157], s[2:3], 0, v[136:137]
	s_add_i32 m0, s28, 0x2000
	s_nop 0
	global_load_lds_dwordx4 v[156:157], off
	v_lshl_add_u64 v[156:157], v[206:207], 0, s[42:43]
	s_mov_b32 m0, s46
	s_nop 0
	global_load_lds_dwordx4 v[156:157], off
	v_lshl_add_u64 v[156:157], v[242:243], 0, s[42:43]
	s_mov_b32 m0, s48
	s_nop 0
	global_load_lds_dwordx4 v[156:157], off
	s_waitcnt vmcnt(8)
	s_waitcnt lgkmcnt(0)
	s_barrier
	s_setprio 1
	v_mfma_f32_16x16x32_bf16 v[62:65], v[140:143], v[184:187], v[62:65]
	v_mfma_f32_16x16x32_bf16 v[58:61], v[148:151], v[184:187], v[58:61]
	v_mfma_f32_16x16x32_bf16 v[46:49], v[140:143], v[192:195], v[46:49]
	v_mfma_f32_16x16x32_bf16 v[42:45], v[148:151], v[192:195], v[42:45]
	v_mfma_f32_16x16x32_bf16 v[30:33], v[140:143], v[226:229], v[30:33]
	v_mfma_f32_16x16x32_bf16 v[26:29], v[148:151], v[226:229], v[26:29]
	v_mfma_f32_16x16x32_bf16 v[14:17], v[140:143], v[234:237], v[14:17]
	v_mfma_f32_16x16x32_bf16 v[10:13], v[148:151], v[234:237], v[10:13]
	v_mfma_f32_16x16x32_bf16 v[62:65], v[144:147], v[188:191], v[62:65]
	v_mfma_f32_16x16x32_bf16 v[58:61], v[152:155], v[188:191], v[58:61]
	v_mfma_f32_16x16x32_bf16 v[46:49], v[144:147], v[196:199], v[46:49]
	v_mfma_f32_16x16x32_bf16 v[42:45], v[152:155], v[196:199], v[42:45]
	v_mfma_f32_16x16x32_bf16 v[30:33], v[144:147], v[230:233], v[30:33]
	v_mfma_f32_16x16x32_bf16 v[26:29], v[152:155], v[230:233], v[26:29]
	v_mfma_f32_16x16x32_bf16 v[14:17], v[144:147], v[238:241], v[14:17]
	v_mfma_f32_16x16x32_bf16 v[10:13], v[152:155], v[238:241], v[10:13]
	v_mfma_f32_16x16x32_bf16 v[54:57], v[168:171], v[184:187], v[54:57]
	v_mfma_f32_16x16x32_bf16 v[50:53], v[176:179], v[184:187], v[50:53]
	v_mfma_f32_16x16x32_bf16 v[38:41], v[168:171], v[192:195], v[38:41]
	v_mfma_f32_16x16x32_bf16 v[34:37], v[176:179], v[192:195], v[34:37]
	v_mfma_f32_16x16x32_bf16 v[22:25], v[168:171], v[226:229], v[22:25]
	v_mfma_f32_16x16x32_bf16 v[18:21], v[176:179], v[226:229], v[18:21]
	v_mfma_f32_16x16x32_bf16 v[6:9], v[168:171], v[234:237], v[6:9]
	v_mfma_f32_16x16x32_bf16 v[2:5], v[176:179], v[234:237], v[2:5]
	v_mfma_f32_16x16x32_bf16 v[54:57], v[172:175], v[188:191], v[54:57]
	v_mfma_f32_16x16x32_bf16 v[50:53], v[180:183], v[188:191], v[50:53]
	v_mfma_f32_16x16x32_bf16 v[38:41], v[172:175], v[196:199], v[38:41]
	v_mfma_f32_16x16x32_bf16 v[34:37], v[180:183], v[196:199], v[34:37]
	v_mfma_f32_16x16x32_bf16 v[22:25], v[172:175], v[230:233], v[22:25]
	v_mfma_f32_16x16x32_bf16 v[18:21], v[180:183], v[230:233], v[18:21]
	v_mfma_f32_16x16x32_bf16 v[6:9], v[172:175], v[238:241], v[6:9]
	v_mfma_f32_16x16x32_bf16 v[2:5], v[180:183], v[238:241], v[2:5]
	s_setprio 0
	s_barrier
	s_cmp_gt_u32 s56, 29
	s_cbranch_scc1 .LBB0_266
	s_mov_b32 s56, s22
	s_branch .LBB0_250

.LBB0_1049:
	s_or_b32 s22, s88, 1
	s_lshl_b64 s[0:1], s[22:23], 7
	s_add_u32 s38, s6, s0
	s_addc_u32 s39, s7, s1
	s_add_i32 s22, s88, 2
	s_lshl_b64 s[0:1], s[22:23], 7
	s_add_u32 s62, s6, s0
	s_addc_u32 s63, s7, s1
	s_and_b64 s[2:3], s[28:29], exec
	s_cselect_b32 s3, s63, s77
	s_cselect_b32 s2, s62, s58
	s_add_u32 s62, s86, s0
	s_addc_u32 s63, s87, s1
	s_and_b64 s[0:1], s[28:29], exec
	s_cselect_b32 s29, s63, s93
	s_cselect_b32 s28, s62, s89
	s_add_i32 s62, 0, 0x10000
	v_add_u32_e32 v145, s62, v142
	s_add_i32 s63, 0, 0x14000
	ds_read_b128 v[136:139], v145
	ds_read_b128 v[146:149], v145 offset:1024
	ds_read_b128 v[150:153], v145 offset:2048
	ds_read_b128 v[154:157], v145 offset:3072
	v_add_u32_e32 v145, s63, v142
	ds_read_b128 v[158:161], v145
	ds_read_b128 v[162:165], v145 offset:1024
	ds_read_b128 v[166:169], v145 offset:2048
	ds_read_b128 v[170:173], v145 offset:3072
	s_add_u32 s0, s38, 0x80000
	s_addc_u32 s1, s39, 0
	s_add_i32 m0, s95, 0xc000
	ds_read_b128 v[174:177], v144
	ds_read_b128 v[178:181], v144 offset:1024
	ds_read_b128 v[182:185], v144 offset:2048
	ds_read_b128 v[186:189], v144 offset:3072
	ds_read_b128 v[190:193], v144 offset:4096
	ds_read_b128 v[194:197], v144 offset:5120
	ds_read_b128 v[198:201], v144 offset:6144
	ds_read_b128 v[226:229], v144 offset:7168
	global_load_lds_dwordx4 v130, s[0:1]
	s_add_i32 m0, s95, 0xe000
	s_nop 0
	global_load_lds_dwordx4 v132, s[0:1]
	s_waitcnt vmcnt(8)
	s_waitcnt lgkmcnt(0)
	s_barrier
	s_setprio 1
	v_mfma_f32_16x16x32_bf16 v[126:129], v[136:139], v[174:177], v[126:129]
	v_mfma_f32_16x16x32_bf16 v[114:117], v[150:153], v[174:177], v[114:117]
	v_mfma_f32_16x16x32_bf16 v[110:113], v[136:139], v[182:185], v[110:113]
	v_mfma_f32_16x16x32_bf16 v[98:101], v[150:153], v[182:185], v[98:101]
	v_mfma_f32_16x16x32_bf16 v[94:97], v[136:139], v[190:193], v[94:97]
	v_mfma_f32_16x16x32_bf16 v[82:85], v[150:153], v[190:193], v[82:85]
	v_mfma_f32_16x16x32_bf16 v[78:81], v[136:139], v[198:201], v[78:81]
	v_mfma_f32_16x16x32_bf16 v[66:69], v[150:153], v[198:201], v[66:69]
	v_mfma_f32_16x16x32_bf16 v[126:129], v[146:149], v[178:181], v[126:129]
	v_mfma_f32_16x16x32_bf16 v[114:117], v[154:157], v[178:181], v[114:117]
	v_mfma_f32_16x16x32_bf16 v[110:113], v[146:149], v[186:189], v[110:113]
	v_mfma_f32_16x16x32_bf16 v[98:101], v[154:157], v[186:189], v[98:101]
	v_mfma_f32_16x16x32_bf16 v[94:97], v[146:149], v[194:197], v[94:97]
	v_mfma_f32_16x16x32_bf16 v[82:85], v[154:157], v[194:197], v[82:85]
	v_mfma_f32_16x16x32_bf16 v[78:81], v[146:149], v[226:229], v[78:81]
	v_mfma_f32_16x16x32_bf16 v[66:69], v[154:157], v[226:229], v[66:69]
	v_mfma_f32_16x16x32_bf16 v[122:125], v[158:161], v[174:177], v[122:125]
	v_mfma_f32_16x16x32_bf16 v[118:121], v[166:169], v[174:177], v[118:121]
	v_mfma_f32_16x16x32_bf16 v[106:109], v[158:161], v[182:185], v[106:109]
	v_mfma_f32_16x16x32_bf16 v[102:105], v[166:169], v[182:185], v[102:105]
	v_mfma_f32_16x16x32_bf16 v[90:93], v[158:161], v[190:193], v[90:93]
	v_mfma_f32_16x16x32_bf16 v[86:89], v[166:169], v[190:193], v[86:89]
	v_mfma_f32_16x16x32_bf16 v[74:77], v[158:161], v[198:201], v[74:77]
	v_mfma_f32_16x16x32_bf16 v[70:73], v[166:169], v[198:201], v[70:73]
	v_mfma_f32_16x16x32_bf16 v[122:125], v[162:165], v[178:181], v[122:125]
	v_mfma_f32_16x16x32_bf16 v[118:121], v[170:173], v[178:181], v[118:121]
	v_mfma_f32_16x16x32_bf16 v[106:109], v[162:165], v[186:189], v[106:109]
	v_mfma_f32_16x16x32_bf16 v[102:105], v[170:173], v[186:189], v[102:105]
	v_mfma_f32_16x16x32_bf16 v[90:93], v[162:165], v[194:197], v[90:93]
	v_mfma_f32_16x16x32_bf16 v[86:89], v[170:173], v[194:197], v[86:89]
	v_mfma_f32_16x16x32_bf16 v[74:77], v[162:165], v[226:229], v[74:77]
	v_mfma_f32_16x16x32_bf16 v[70:73], v[170:173], v[226:229], v[70:73]
	s_setprio 0
	s_barrier
	s_add_i32 s0, s62, s75
	v_lshl_add_u64 v[206:207], s[28:29], 0, v[202:203]
	s_mov_b32 m0, s0
	ds_read_b128 v[174:177], v144 offset:16384
	ds_read_b128 v[178:181], v144 offset:17408
	ds_read_b128 v[182:185], v144 offset:18432
	ds_read_b128 v[186:189], v144 offset:19456
	ds_read_b128 v[190:193], v144 offset:20480
	ds_read_b128 v[194:197], v144 offset:21504
	ds_read_b128 v[198:201], v144 offset:22528
	ds_read_b128 v[226:229], v144 offset:23552
	global_load_lds_dwordx4 v[206:207], off
	s_add_i32 m0, s0, 0x2000
	s_add_u32 s0, s28, 0x80000
	v_lshl_add_u64 v[230:231], s[28:29], 0, v[134:135]
	s_addc_u32 s1, s29, 0
	s_add_i32 s38, s63, s75
	global_load_lds_dwordx4 v[230:231], off
	v_lshl_add_u64 v[232:233], s[0:1], 0, v[202:203]
	s_mov_b32 m0, s38
	v_lshl_add_u64 v[234:235], s[2:3], 0, v[132:133]
	global_load_lds_dwordx4 v[232:233], off
	v_lshl_add_u64 v[232:233], s[0:1], 0, v[134:135]
	s_add_i32 m0, s38, 0x2000
	s_nop 0
	global_load_lds_dwordx4 v[232:233], off
	v_lshl_add_u64 v[232:233], s[2:3], 0, v[130:131]
	s_mov_b32 m0, s95
	s_nop 0
	global_load_lds_dwordx4 v[232:233], off
	s_mov_b32 m0, s97
	s_nop 0
	global_load_lds_dwordx4 v[234:235], off
	s_waitcnt vmcnt(8)
	s_waitcnt lgkmcnt(0)
	s_barrier
	s_setprio 1
	v_mfma_f32_16x16x32_bf16 v[62:65], v[136:139], v[174:177], v[62:65]
	v_mfma_f32_16x16x32_bf16 v[50:53], v[150:153], v[174:177], v[50:53]
	v_mfma_f32_16x16x32_bf16 v[46:49], v[136:139], v[182:185], v[46:49]
	v_mfma_f32_16x16x32_bf16 v[34:37], v[150:153], v[182:185], v[34:37]
	v_mfma_f32_16x16x32_bf16 v[30:33], v[136:139], v[190:193], v[30:33]
	v_mfma_f32_16x16x32_bf16 v[18:21], v[150:153], v[190:193], v[18:21]
	v_mfma_f32_16x16x32_bf16 v[14:17], v[136:139], v[198:201], v[14:17]
	v_mfma_f32_16x16x32_bf16 v[6:9], v[150:153], v[198:201], v[6:9]
	v_mfma_f32_16x16x32_bf16 v[62:65], v[146:149], v[178:181], v[62:65]
	v_mfma_f32_16x16x32_bf16 v[50:53], v[154:157], v[178:181], v[50:53]
	v_mfma_f32_16x16x32_bf16 v[46:49], v[146:149], v[186:189], v[46:49]
	v_mfma_f32_16x16x32_bf16 v[34:37], v[154:157], v[186:189], v[34:37]
	v_mfma_f32_16x16x32_bf16 v[30:33], v[146:149], v[194:197], v[30:33]
	v_mfma_f32_16x16x32_bf16 v[18:21], v[154:157], v[194:197], v[18:21]
	v_mfma_f32_16x16x32_bf16 v[14:17], v[146:149], v[226:229], v[14:17]
	v_mfma_f32_16x16x32_bf16 v[6:9], v[154:157], v[226:229], v[6:9]
	v_mfma_f32_16x16x32_bf16 v[58:61], v[158:161], v[174:177], v[58:61]
	v_mfma_f32_16x16x32_bf16 v[54:57], v[166:169], v[174:177], v[54:57]
	v_mfma_f32_16x16x32_bf16 v[42:45], v[158:161], v[182:185], v[42:45]
	v_mfma_f32_16x16x32_bf16 v[38:41], v[166:169], v[182:185], v[38:41]
	v_mfma_f32_16x16x32_bf16 v[26:29], v[158:161], v[190:193], v[26:29]
	v_mfma_f32_16x16x32_bf16 v[22:25], v[166:169], v[190:193], v[22:25]
	v_mfma_f32_16x16x32_bf16 v[10:13], v[158:161], v[198:201], v[10:13]
	v_mfma_f32_16x16x32_bf16 v[2:5], v[166:169], v[198:201], v[2:5]
	v_mfma_f32_16x16x32_bf16 v[58:61], v[162:165], v[178:181], v[58:61]
	v_mfma_f32_16x16x32_bf16 v[54:57], v[170:173], v[178:181], v[54:57]
	v_mfma_f32_16x16x32_bf16 v[42:45], v[162:165], v[186:189], v[42:45]
	v_mfma_f32_16x16x32_bf16 v[38:41], v[170:173], v[186:189], v[38:41]
	v_mfma_f32_16x16x32_bf16 v[26:29], v[162:165], v[194:197], v[26:29]
	v_mfma_f32_16x16x32_bf16 v[22:25], v[170:173], v[194:197], v[22:25]
	v_mfma_f32_16x16x32_bf16 v[10:13], v[162:165], v[226:229], v[10:13]
	v_mfma_f32_16x16x32_bf16 v[2:5], v[170:173], v[226:229], v[2:5]
	s_setprio 0
	s_barrier
	s_add_i32 s38, 0, 0x18000
	v_add_u32_e32 v145, s38, v142
	s_add_i32 s39, 0, 0x1c000
	ds_read_b128 v[136:139], v145
	ds_read_b128 v[146:149], v145 offset:1024
	ds_read_b128 v[150:153], v145 offset:2048
	ds_read_b128 v[154:157], v145 offset:3072
	v_add_u32_e32 v145, s39, v142
	ds_read_b128 v[158:161], v145
	ds_read_b128 v[162:165], v145 offset:1024
	ds_read_b128 v[166:169], v145 offset:2048
	ds_read_b128 v[170:173], v145 offset:3072
	s_add_u32 s0, s2, 0x80000
	s_addc_u32 s1, s3, 0
	s_mov_b32 m0, s46
	ds_read_b128 v[174:177], v144 offset:32768
	ds_read_b128 v[178:181], v144 offset:33792
	ds_read_b128 v[182:185], v144 offset:34816
	ds_read_b128 v[186:189], v144 offset:35840
	ds_read_b128 v[190:193], v144 offset:36864
	ds_read_b128 v[194:197], v144 offset:37888
	ds_read_b128 v[198:201], v144 offset:38912
	ds_read_b128 v[226:229], v144 offset:39936
	global_load_lds_dwordx4 v130, s[0:1]
	s_mov_b32 m0, s48
	s_nop 0
	global_load_lds_dwordx4 v132, s[0:1]
	s_waitcnt vmcnt(8)
	s_waitcnt lgkmcnt(0)
	s_barrier
	s_setprio 1
	v_mfma_f32_16x16x32_bf16 v[126:129], v[136:139], v[174:177], v[126:129]
	v_mfma_f32_16x16x32_bf16 v[114:117], v[150:153], v[174:177], v[114:117]
	v_mfma_f32_16x16x32_bf16 v[110:113], v[136:139], v[182:185], v[110:113]
	v_mfma_f32_16x16x32_bf16 v[98:101], v[150:153], v[182:185], v[98:101]
	v_mfma_f32_16x16x32_bf16 v[94:97], v[136:139], v[190:193], v[94:97]
	v_mfma_f32_16x16x32_bf16 v[82:85], v[150:153], v[190:193], v[82:85]
	v_mfma_f32_16x16x32_bf16 v[78:81], v[136:139], v[198:201], v[78:81]
	v_mfma_f32_16x16x32_bf16 v[66:69], v[150:153], v[198:201], v[66:69]
	v_mfma_f32_16x16x32_bf16 v[126:129], v[146:149], v[178:181], v[126:129]
	v_mfma_f32_16x16x32_bf16 v[114:117], v[154:157], v[178:181], v[114:117]
	v_mfma_f32_16x16x32_bf16 v[110:113], v[146:149], v[186:189], v[110:113]
	v_mfma_f32_16x16x32_bf16 v[98:101], v[154:157], v[186:189], v[98:101]
	v_mfma_f32_16x16x32_bf16 v[94:97], v[146:149], v[194:197], v[94:97]
	v_mfma_f32_16x16x32_bf16 v[82:85], v[154:157], v[194:197], v[82:85]
	v_mfma_f32_16x16x32_bf16 v[78:81], v[146:149], v[226:229], v[78:81]
	v_mfma_f32_16x16x32_bf16 v[66:69], v[154:157], v[226:229], v[66:69]
	v_mfma_f32_16x16x32_bf16 v[122:125], v[158:161], v[174:177], v[122:125]
	v_mfma_f32_16x16x32_bf16 v[118:121], v[166:169], v[174:177], v[118:121]
	v_mfma_f32_16x16x32_bf16 v[106:109], v[158:161], v[182:185], v[106:109]
	v_mfma_f32_16x16x32_bf16 v[102:105], v[166:169], v[182:185], v[102:105]
	v_mfma_f32_16x16x32_bf16 v[90:93], v[158:161], v[190:193], v[90:93]
	v_mfma_f32_16x16x32_bf16 v[86:89], v[166:169], v[190:193], v[86:89]
	v_mfma_f32_16x16x32_bf16 v[74:77], v[158:161], v[198:201], v[74:77]
	v_mfma_f32_16x16x32_bf16 v[70:73], v[166:169], v[198:201], v[70:73]
	v_mfma_f32_16x16x32_bf16 v[122:125], v[162:165], v[178:181], v[122:125]
	v_mfma_f32_16x16x32_bf16 v[118:121], v[170:173], v[178:181], v[118:121]
	v_mfma_f32_16x16x32_bf16 v[106:109], v[162:165], v[186:189], v[106:109]
	v_mfma_f32_16x16x32_bf16 v[102:105], v[170:173], v[186:189], v[102:105]
	v_mfma_f32_16x16x32_bf16 v[90:93], v[162:165], v[194:197], v[90:93]
	v_mfma_f32_16x16x32_bf16 v[86:89], v[170:173], v[194:197], v[86:89]
	v_mfma_f32_16x16x32_bf16 v[74:77], v[162:165], v[226:229], v[74:77]
	v_mfma_f32_16x16x32_bf16 v[70:73], v[170:173], v[226:229], v[70:73]
	s_setprio 0
	s_barrier
	s_add_i32 s0, s38, s75
	v_lshl_add_u64 v[206:207], v[206:207], 0, s[42:43]
	s_mov_b32 m0, s0
	ds_read_b128 v[174:177], v144 offset:49152
	ds_read_b128 v[178:181], v144 offset:50176
	ds_read_b128 v[182:185], v144 offset:51200
	ds_read_b128 v[186:189], v144 offset:52224
	ds_read_b128 v[190:193], v144 offset:53248
	ds_read_b128 v[194:197], v144 offset:54272
	ds_read_b128 v[198:201], v144 offset:55296
	ds_read_b128 v[226:229], v144 offset:56320
	global_load_lds_dwordx4 v[206:207], off
	s_add_i32 m0, s0, 0x2000
	s_add_u32 s0, s28, 0x80080
	v_lshl_add_u64 v[206:207], v[230:231], 0, s[42:43]
	s_addc_u32 s1, s29, 0
	s_add_i32 s2, s39, s75
	global_load_lds_dwordx4 v[206:207], off
	v_lshl_add_u64 v[206:207], s[0:1], 0, v[202:203]
	s_mov_b32 m0, s2
	s_nop 0
	global_load_lds_dwordx4 v[206:207], off
	v_lshl_add_u64 v[206:207], s[0:1], 0, v[134:135]
	s_add_i32 m0, s2, 0x2000
	s_nop 0
	global_load_lds_dwordx4 v[206:207], off
	v_lshl_add_u64 v[206:207], v[232:233], 0, s[42:43]
	s_mov_b32 m0, s30
	s_nop 0
	global_load_lds_dwordx4 v[206:207], off
	v_lshl_add_u64 v[206:207], v[234:235], 0, s[42:43]
	s_mov_b32 m0, s31
	s_nop 0
	global_load_lds_dwordx4 v[206:207], off
	s_waitcnt vmcnt(8)
	s_waitcnt lgkmcnt(0)
	s_barrier
	s_setprio 1
	v_mfma_f32_16x16x32_bf16 v[62:65], v[136:139], v[174:177], v[62:65]
	v_mfma_f32_16x16x32_bf16 v[50:53], v[150:153], v[174:177], v[50:53]
	v_mfma_f32_16x16x32_bf16 v[46:49], v[136:139], v[182:185], v[46:49]
	v_mfma_f32_16x16x32_bf16 v[34:37], v[150:153], v[182:185], v[34:37]
	v_mfma_f32_16x16x32_bf16 v[30:33], v[136:139], v[190:193], v[30:33]
	v_mfma_f32_16x16x32_bf16 v[18:21], v[150:153], v[190:193], v[18:21]
	v_mfma_f32_16x16x32_bf16 v[14:17], v[136:139], v[198:201], v[14:17]
	v_mfma_f32_16x16x32_bf16 v[6:9], v[150:153], v[198:201], v[6:9]
	v_mfma_f32_16x16x32_bf16 v[62:65], v[146:149], v[178:181], v[62:65]
	v_mfma_f32_16x16x32_bf16 v[50:53], v[154:157], v[178:181], v[50:53]
	v_mfma_f32_16x16x32_bf16 v[46:49], v[146:149], v[186:189], v[46:49]
	v_mfma_f32_16x16x32_bf16 v[34:37], v[154:157], v[186:189], v[34:37]
	v_mfma_f32_16x16x32_bf16 v[30:33], v[146:149], v[194:197], v[30:33]
	v_mfma_f32_16x16x32_bf16 v[18:21], v[154:157], v[194:197], v[18:21]
	v_mfma_f32_16x16x32_bf16 v[14:17], v[146:149], v[226:229], v[14:17]
	v_mfma_f32_16x16x32_bf16 v[6:9], v[154:157], v[226:229], v[6:9]
	v_mfma_f32_16x16x32_bf16 v[58:61], v[158:161], v[174:177], v[58:61]
	v_mfma_f32_16x16x32_bf16 v[54:57], v[166:169], v[174:177], v[54:57]
	v_mfma_f32_16x16x32_bf16 v[42:45], v[158:161], v[182:185], v[42:45]
	v_mfma_f32_16x16x32_bf16 v[38:41], v[166:169], v[182:185], v[38:41]
	v_mfma_f32_16x16x32_bf16 v[26:29], v[158:161], v[190:193], v[26:29]
	v_mfma_f32_16x16x32_bf16 v[22:25], v[166:169], v[190:193], v[22:25]
	v_mfma_f32_16x16x32_bf16 v[10:13], v[158:161], v[198:201], v[10:13]
	v_mfma_f32_16x16x32_bf16 v[2:5], v[166:169], v[198:201], v[2:5]
	v_mfma_f32_16x16x32_bf16 v[58:61], v[162:165], v[178:181], v[58:61]
	v_mfma_f32_16x16x32_bf16 v[54:57], v[170:173], v[178:181], v[54:57]
	v_mfma_f32_16x16x32_bf16 v[42:45], v[162:165], v[186:189], v[42:45]
	v_mfma_f32_16x16x32_bf16 v[38:41], v[170:173], v[186:189], v[38:41]
	v_mfma_f32_16x16x32_bf16 v[26:29], v[162:165], v[194:197], v[26:29]
	v_mfma_f32_16x16x32_bf16 v[22:25], v[170:173], v[194:197], v[22:25]
	v_mfma_f32_16x16x32_bf16 v[10:13], v[162:165], v[226:229], v[10:13]
	v_mfma_f32_16x16x32_bf16 v[2:5], v[170:173], v[226:229], v[2:5]
	s_setprio 0
	s_barrier
	s_cmp_gt_u32 s88, 29
	s_mov_b32 s88, s22
	s_cbranch_scc1 .LBB0_1061
